# token-prep phase: 1/x and 2/x in the sigmoid/tanh gates use v_rcp_f32 (f32 reciprocal) instead of the 11-instruction IEEE division sequence, as already done for the merge gates
# speedup vs baseline: 1.0022x; 1.0022x over previous
; DI float bf2f(u16 h) { return __uint_as_float(((unsigned)h) << 16); }
; DI u16 f2bf(float a) { return (u16)(pack2(a, 0.f) & 0xffffu); }
; DI float sigmoidf_(float x) { return 1.f / (1.f + __expf(-x)); }
; DI void phase_tokB(const Params& p, int l, char* smem) {
;     ...
;     for (int e = tid; e < 16 * 384; e += 256) {
;       const int i = e / 384, c = e - i * 384, zc = 768 + c;
;       const float z = bf2f(Zs[(i + 1) * ZSL + zc]), zp = bf2f(Zs[i * ZSL + zc]), zn = bf2f(Zs[(i + 2) * ZSL + zc]);
;       float v = z + mu0[zc] * (zp - z) + mu1[zc] * (zn - z);
;       if (c < 128) v = 1.f - 2.f / (1.f + __expf(2.f * v)); else if (c >= 256) v = sigmoidf_(v);
;       TA[i * TAL + c] = f2bf(v);
;     }
.LBB0_800:
	v_mul_hi_i32 v4, v2, s73
	v_lshrrev_b32_e32 v5, 31, v4
	v_ashrrev_i32_e32 v4, 6, v4
	v_add_u32_e32 v4, v4, v5
	v_mad_i32_i24 v8, v4, s30, v2
	v_lshlrev_b32_e32 v5, 1, v8
	v_mad_i32_i24 v6, v4, s80, v5
	ds_read_u16 v7, v6 offset:3856
	ds_read_u16 v9, v6 offset:6176
	ds_read_u16 v12, v6 offset:1536
	v_add_u32_e32 v6, v5, v5
	v_add_u32_e32 v10, 32, v6
	ds_read2st64_b32 v[10:11], v10 offset0:224 offset1:242
	s_waitcnt lgkmcnt(3)
	v_lshlrev_b32_e32 v7, 16, v7
	s_waitcnt lgkmcnt(1)
	v_lshlrev_b32_e32 v12, 16, v12
	v_lshlrev_b32_e32 v9, 16, v9
	v_sub_f32_e32 v12, v12, v7
	v_sub_f32_e32 v9, v9, v7
	s_waitcnt lgkmcnt(0)
	v_fmac_f32_e32 v7, v10, v12
	v_fmac_f32_e32 v7, v11, v9
	v_cmp_lt_i32_e32 vcc, s78, v8
	s_and_saveexec_b64 s[40:41], vcc
	s_xor_b64 s[40:41], exec, s[40:41]
	s_cbranch_execz .LBB0_804
	s_movk_i32 s42, 0xff
	v_cmp_lt_u32_e32 vcc, s42, v8
	s_and_saveexec_b64 s[42:43], vcc
	s_cbranch_execz .LBB0_803
	v_mul_f32_e32 v7, 0xbfb8aa3b, v7
	v_exp_f32_e32 v7, v7
	s_nop 0
	v_add_f32_e32 v7, 1.0, v7
	v_rcp_f32_e32 v7, v7

; DI float bf2f(u16 h) { return __uint_as_float(((unsigned)h) << 16); }
; DI u16 f2bf(float a) { return (u16)(pack2(a, 0.f) & 0xffffu); }
; DI float sigmoidf_(float x) { return 1.f / (1.f + __expf(-x)); }
; DI void phase_tokB(const Params& p, int l, char* smem) {
;     ...
;     for (int e = tid; e < 16 * 384; e += 256) {
;       const int i = e / 384, c = e - i * 384, zc = 768 + c;
;       const float z = bf2f(Zs[(i + 1) * ZSL + zc]), zp = bf2f(Zs[i * ZSL + zc]), zn = bf2f(Zs[(i + 2) * ZSL + zc]);
;       float v = z + mu0[zc] * (zp - z) + mu1[zc] * (zn - z);
;       if (c < 128) v = 1.f - 2.f / (1.f + __expf(2.f * v)); else if (c >= 256) v = sigmoidf_(v);
;       TA[i * TAL + c] = f2bf(v);
;     }
.LBB0_804:
	s_andn2_saveexec_b64 s[40:41], s[40:41]
	s_cbranch_execz .LBB0_799
	v_add_f32_e32 v7, v7, v7
	v_mul_f32_e32 v7, 0x3fb8aa3b, v7
	v_exp_f32_e32 v7, v7
	s_nop 0
	v_add_f32_e32 v7, 1.0, v7
	v_rcp_f32_e32 v7, v7
	s_nop 0
	v_add_f32_e32 v7, v7, v7
	v_sub_f32_e32 v7, 1.0, v7
	s_branch .LBB0_799

; DI float bf2f(u16 h) { return __uint_as_float(((unsigned)h) << 16); }
; DI u16 f2bf(float a) { return (u16)(pack2(a, 0.f) & 0xffffu); }
; DI float sigmoidf_(float x) { return 1.f / (1.f + __expf(-x)); }
; DI void phase_tokB(const Params& p, int l, char* smem) {
;     ...
;     for (int e = tid; e < 16 * 384; e += 256) {
;       const int i = e / 384, c = e - i * 384, zc = 768 + c;
;       const float z = bf2f(Zs[(i + 1) * ZSL + zc]), zp = bf2f(Zs[i * ZSL + zc]), zn = bf2f(Zs[(i + 2) * ZSL + zc]);
;       float v = z + mu0[zc] * (zp - z) + mu1[zc] * (zn - z);
;       if (c < 128) v = 1.f - 2.f / (1.f + __expf(2.f * v)); else if (c >= 256) v = sigmoidf_(v);
;       TA[i * TAL + c] = f2bf(v);
;     }
.LBB0_820:
	v_mul_hi_i32 v3, v2, s73
	v_lshrrev_b32_e32 v4, 31, v3
	v_ashrrev_i32_e32 v3, 6, v3
	v_add_u32_e32 v3, v3, v4
	v_mad_i32_i24 v7, v3, s30, v2
	v_lshlrev_b32_e32 v4, 1, v7
	v_mad_i32_i24 v5, v3, s80, v4
	ds_read_u16 v6, v5 offset:3856
	ds_read_u16 v10, v5 offset:6176
	ds_read_u16 v11, v5 offset:1536
	v_add_u32_e32 v5, v4, v4
	v_add_u32_e32 v8, 32, v5
	ds_read2st64_b32 v[8:9], v8 offset0:224 offset1:242
	s_waitcnt lgkmcnt(3)
	v_lshlrev_b32_e32 v6, 16, v6
	s_waitcnt lgkmcnt(1)
	v_lshlrev_b32_e32 v11, 16, v11
	v_lshlrev_b32_e32 v10, 16, v10
	v_sub_f32_e32 v11, v11, v6
	v_sub_f32_e32 v10, v10, v6
	s_waitcnt lgkmcnt(0)
	v_fmac_f32_e32 v6, v8, v11
	v_fmac_f32_e32 v6, v9, v10
	v_cmp_lt_i32_e32 vcc, s78, v7
	s_and_saveexec_b64 s[38:39], vcc
	s_xor_b64 s[38:39], exec, s[38:39]
	s_cbranch_execz .LBB0_824
	s_movk_i32 s40, 0xff
	v_cmp_lt_u32_e32 vcc, s40, v7
	s_and_saveexec_b64 s[40:41], vcc
	s_cbranch_execz .LBB0_823
	v_mul_f32_e32 v6, 0xbfb8aa3b, v6
	v_exp_f32_e32 v6, v6
	s_nop 0
	v_add_f32_e32 v6, 1.0, v6
	v_rcp_f32_e32 v6, v6

; DI float bf2f(u16 h) { return __uint_as_float(((unsigned)h) << 16); }
; DI u16 f2bf(float a) { return (u16)(pack2(a, 0.f) & 0xffffu); }
; DI float sigmoidf_(float x) { return 1.f / (1.f + __expf(-x)); }
; DI void phase_tokB(const Params& p, int l, char* smem) {
;     ...
;     for (int e = tid; e < 16 * 384; e += 256) {
;       const int i = e / 384, c = e - i * 384, zc = 768 + c;
;       const float z = bf2f(Zs[(i + 1) * ZSL + zc]), zp = bf2f(Zs[i * ZSL + zc]), zn = bf2f(Zs[(i + 2) * ZSL + zc]);
;       float v = z + mu0[zc] * (zp - z) + mu1[zc] * (zn - z);
;       if (c < 128) v = 1.f - 2.f / (1.f + __expf(2.f * v)); else if (c >= 256) v = sigmoidf_(v);
;       TA[i * TAL + c] = f2bf(v);
;     }
.LBB0_824:
	s_andn2_saveexec_b64 s[38:39], s[38:39]
	s_cbranch_execz .LBB0_826
	v_add_f32_e32 v6, v6, v6
	v_mul_f32_e32 v6, 0x3fb8aa3b, v6
	v_exp_f32_e32 v6, v6
	s_nop 0
	v_add_f32_e32 v6, 1.0, v6
	v_rcp_f32_e32 v6, v6
	s_nop 0
	v_add_f32_e32 v6, v6, v6
	v_sub_f32_e32 v6, 1.0, v6
.LBB0_826:
	s_or_b64 exec, exec, s[38:39]
	v_sub_u32_e32 v4, v5, v4
	s_movk_i32 s38, 0x310
	v_cvt_pk_bf16_f32 v6, v6, s0
	v_mad_i32_i24 v3, v3, s38, v4
	ds_write_b16 v3, v6 offset:41760
	v_add_u32_e32 v3, 0x100, v2
	v_mul_hi_i32 v4, v3, s73
	v_lshrrev_b32_e32 v5, 31, v4
	v_ashrrev_i32_e32 v4, 6, v4
	v_add_u32_e32 v4, v4, v5
	v_mad_i32_i24 v5, v4, s30, v2
	v_add_u32_e32 v8, 0x300, v5
	v_mul_i32_i24_e32 v6, 0x910, v4
	v_lshl_add_u32 v6, v8, 1, v6
	ds_read_u16 v9, v6 offset:2832
	ds_read_u16 v10, v6 offset:5152
	ds_read_u16 v11, v6 offset:512
	v_lshlrev_b32_e32 v8, 2, v8
	v_add_u32_e32 v8, 32, v8
	v_add_u32_e32 v7, 0x100, v5
	s_waitcnt lgkmcnt(2)
	v_lshlrev_b32_e32 v6, 16, v9
	ds_read2st64_b32 v[8:9], v8 offset0:216 offset1:234
	s_waitcnt lgkmcnt(1)
	v_lshlrev_b32_e32 v11, 16, v11
	v_lshlrev_b32_e32 v10, 16, v10
	v_sub_f32_e32 v11, v11, v6
	v_sub_f32_e32 v10, v10, v6
	s_waitcnt lgkmcnt(0)
	v_fmac_f32_e32 v6, v8, v11
	v_fmac_f32_e32 v6, v9, v10
	v_cmp_lt_i32_e32 vcc, s78, v7
	s_and_saveexec_b64 s[38:39], vcc
	s_xor_b64 s[38:39], exec, s[38:39]
	s_cbranch_execz .LBB0_830
	s_movk_i32 s40, 0xff
	v_cmp_lt_u32_e32 vcc, s40, v7
	s_and_saveexec_b64 s[40:41], vcc
	s_cbranch_execz .LBB0_829
	v_mul_f32_e32 v6, 0xbfb8aa3b, v6
	v_exp_f32_e32 v6, v6
	s_nop 0
	v_add_f32_e32 v6, 1.0, v6
	v_rcp_f32_e32 v6, v6

; DI float bf2f(u16 h) { return __uint_as_float(((unsigned)h) << 16); }
; DI u16 f2bf(float a) { return (u16)(pack2(a, 0.f) & 0xffffu); }
; DI float sigmoidf_(float x) { return 1.f / (1.f + __expf(-x)); }
; DI void phase_tokB(const Params& p, int l, char* smem) {
;     ...
;     for (int e = tid; e < 16 * 384; e += 256) {
;       const int i = e / 384, c = e - i * 384, zc = 768 + c;
;       const float z = bf2f(Zs[(i + 1) * ZSL + zc]), zp = bf2f(Zs[i * ZSL + zc]), zn = bf2f(Zs[(i + 2) * ZSL + zc]);
;       float v = z + mu0[zc] * (zp - z) + mu1[zc] * (zn - z);
;       if (c < 128) v = 1.f - 2.f / (1.f + __expf(2.f * v)); else if (c >= 256) v = sigmoidf_(v);
;       TA[i * TAL + c] = f2bf(v);
;     }
.LBB0_832:
	s_or_b64 exec, exec, s[38:39]
	v_mul_i32_i24_e32 v4, 0x310, v4
	v_cvt_pk_bf16_f32 v6, v6, s0
	v_lshl_add_u32 v4, v5, 1, v4
	v_add_u32_e32 v3, 0x100, v3
	ds_write_b16 v4, v6 offset:42272
	v_mul_hi_i32 v4, v3, s73
	v_lshrrev_b32_e32 v5, 31, v4
	v_ashrrev_i32_e32 v4, 6, v4
	v_add_u32_e32 v4, v4, v5
	v_mad_i32_i24 v5, v4, s30, v2
	v_add_u32_e32 v8, 0x300, v5
	v_mul_i32_i24_e32 v6, 0x910, v4
	v_lshl_add_u32 v6, v8, 1, v6
	ds_read_u16 v9, v6 offset:3344
	ds_read_u16 v10, v6 offset:5664
	ds_read_u16 v11, v6 offset:1024
	v_lshlrev_b32_e32 v8, 2, v8
	v_add_u32_e32 v8, 32, v8
	v_add_u32_e32 v7, 0x200, v5
	s_waitcnt lgkmcnt(2)
	v_lshlrev_b32_e32 v6, 16, v9
	ds_read2st64_b32 v[8:9], v8 offset0:220 offset1:238
	s_waitcnt lgkmcnt(1)
	v_lshlrev_b32_e32 v11, 16, v11
	v_lshlrev_b32_e32 v10, 16, v10
	v_sub_f32_e32 v11, v11, v6
	v_sub_f32_e32 v10, v10, v6
	s_waitcnt lgkmcnt(0)
	v_fmac_f32_e32 v6, v8, v11
	v_fmac_f32_e32 v6, v9, v10
	v_cmp_lt_i32_e32 vcc, s78, v7
	s_and_saveexec_b64 s[38:39], vcc
	s_xor_b64 s[38:39], exec, s[38:39]
	s_cbranch_execz .LBB0_836
	s_movk_i32 s40, 0xff
	v_cmp_lt_u32_e32 vcc, s40, v7
	s_and_saveexec_b64 s[40:41], vcc
	s_cbranch_execz .LBB0_835
	v_mul_f32_e32 v6, 0xbfb8aa3b, v6
	v_exp_f32_e32 v6, v6
	s_nop 0
	v_add_f32_e32 v6, 1.0, v6
	v_rcp_f32_e32 v6, v6

; DI float bf2f(u16 h) { return __uint_as_float(((unsigned)h) << 16); }
; DI u16 f2bf(float a) { return (u16)(pack2(a, 0.f) & 0xffffu); }
; DI float sigmoidf_(float x) { return 1.f / (1.f + __expf(-x)); }
; DI void phase_tokB(const Params& p, int l, char* smem) {
;     ...
;     for (int e = tid; e < 16 * 384; e += 256) {
;       const int i = e / 384, c = e - i * 384, zc = 768 + c;
;       const float z = bf2f(Zs[(i + 1) * ZSL + zc]), zp = bf2f(Zs[i * ZSL + zc]), zn = bf2f(Zs[(i + 2) * ZSL + zc]);
;       float v = z + mu0[zc] * (zp - z) + mu1[zc] * (zn - z);
;       if (c < 128) v = 1.f - 2.f / (1.f + __expf(2.f * v)); else if (c >= 256) v = sigmoidf_(v);
;       TA[i * TAL + c] = f2bf(v);
;     }
.LBB0_838:
	s_or_b64 exec, exec, s[38:39]
	v_mul_i32_i24_e32 v4, 0x310, v4
	v_add_u32_e32 v3, 0x100, v3
	v_cvt_pk_bf16_f32 v6, v6, s0
	v_lshl_add_u32 v4, v5, 1, v4
	v_mul_hi_i32 v3, v3, s73
	ds_write_b16 v4, v6 offset:42784
	v_lshrrev_b32_e32 v4, 31, v3
	v_ashrrev_i32_e32 v3, 6, v3
	v_add_u32_e32 v3, v3, v4
	v_mad_i32_i24 v4, v3, s30, v2
	v_add_u32_e32 v6, 0x300, v4
	v_mul_i32_i24_e32 v5, 0x910, v3
	v_lshl_add_u32 v5, v6, 1, v5
	ds_read_u16 v7, v5 offset:3856
	ds_read_u16 v10, v5 offset:6176
	ds_read_u16 v11, v5 offset:1536
	v_cmp_lt_i32_e32 vcc, s78, v6
	s_waitcnt lgkmcnt(2)
	v_lshlrev_b32_e32 v5, 16, v7
	v_lshlrev_b32_e32 v7, 2, v6
	v_add_u32_e32 v7, 32, v7
	ds_read2st64_b32 v[8:9], v7 offset0:224 offset1:242
	s_waitcnt lgkmcnt(1)
	v_lshlrev_b32_e32 v7, 16, v11
	v_lshlrev_b32_e32 v10, 16, v10
	v_sub_f32_e32 v7, v7, v5
	v_sub_f32_e32 v10, v10, v5
	s_waitcnt lgkmcnt(0)
	v_fmac_f32_e32 v5, v8, v7
	v_fmac_f32_e32 v5, v9, v10
	s_and_saveexec_b64 s[38:39], vcc
	s_xor_b64 s[38:39], exec, s[38:39]
	s_cbranch_execz .LBB0_842
	s_movk_i32 s40, 0xff
	v_cmp_lt_u32_e32 vcc, s40, v6
	s_and_saveexec_b64 s[40:41], vcc
	s_cbranch_execz .LBB0_841
	v_mul_f32_e32 v5, 0xbfb8aa3b, v5
	v_exp_f32_e32 v5, v5
	s_nop 0
	v_add_f32_e32 v5, 1.0, v5
	v_rcp_f32_e32 v5, v5

; DI float bf2f(u16 h) { return __uint_as_float(((unsigned)h) << 16); }
; DI u16 f2bf(float a) { return (u16)(pack2(a, 0.f) & 0xffffu); }
; DI float sigmoidf_(float x) { return 1.f / (1.f + __expf(-x)); }
; DI void phase_tokB(const Params& p, int l, char* smem) {
;     ...
;     for (int e = tid; e < 16 * 384; e += 256) {
;       const int i = e / 384, c = e - i * 384, zc = 768 + c;
;       const float z = bf2f(Zs[(i + 1) * ZSL + zc]), zp = bf2f(Zs[i * ZSL + zc]), zn = bf2f(Zs[(i + 2) * ZSL + zc]);
;       float v = z + mu0[zc] * (zp - z) + mu1[zc] * (zn - z);
;       if (c < 128) v = 1.f - 2.f / (1.f + __expf(2.f * v)); else if (c >= 256) v = sigmoidf_(v);
;       TA[i * TAL + c] = f2bf(v);
;     }
.LBB0_842:
	s_andn2_saveexec_b64 s[38:39], s[38:39]
	s_cbranch_execz .LBB0_819
	v_add_f32_e32 v5, v5, v5
	v_mul_f32_e32 v5, 0x3fb8aa3b, v5
	v_exp_f32_e32 v5, v5
	s_nop 0
	v_add_f32_e32 v5, 1.0, v5
	v_rcp_f32_e32 v5, v5
	s_nop 0
	v_add_f32_e32 v5, v5, v5
	v_sub_f32_e32 v5, 1.0, v5
	s_branch .LBB0_819

; DI void phase_tokB(const Params& p, int l, char* smem) {
;     ...
;     auto product64x2 = [&](f32x4 (&ac0)[4], f32x4 (&ac1)[4], const u16* W0, const u16* W1, int off0, int off1) {
;       bf16x8 a0[2][4], a1[2][4];
; #pragma unroll
;       for (int ks = 0; ks < 2; ++ks)
; #pragma unroll
;         for (int ni = 0; ni < 4; ++ni) {
;           a0[ks][ni] = *(const bf16x8*)(W0 + (size_t)(wave * 64 + ni * 16 + lr) * 64 + ks * 32 + lq * 8);
;           a1[ks][ni] = *(const bf16x8*)(W1 + (size_t)(wave * 64 + ni * 16 + lr) * 64 + ks * 32 + lq * 8);
;         }
; #pragma unroll
;       for (int ni = 0; ni < 4; ++ni) { ac0[ni] = f32x4{0.f, 0.f, 0.f, 0.f}; ac1[ni] = f32x4{0.f, 0.f, 0.f, 0.f}; }
; #pragma unroll
;       for (int ks = 0; ks < 2; ++ks) {
;         const bf16x8 b0 = *(const bf16x8*)(TA + lr * TAL + off0 + ks * 32 + lq * 8);
;         const bf16x8 b1 = *(const bf16x8*)(TA + lr * TAL + off1 + ks * 32 + lq * 8);
; #pragma unroll
;         for (int ni = 0; ni < 4; ++ni) {
;           ac0[ni] = __builtin_amdgcn_mfma_f32_16x16x32_bf16(a0[ks][ni], b0, ac0[ni], 0, 0, 0);
;           ac1[ni] = __builtin_amdgcn_mfma_f32_16x16x32_bf16(a1[ks][ni], b1, ac1[ni], 0, 0, 0);
;         }
;       }
;       __builtin_amdgcn_sched_barrier(0);
;     };
;     ...
;       for (int ni = 0; ni < 4; ++ni) {
;         const int ch = wave * 64 + ni * 16 + lq * 4;
;         const size_t o = (size_t)row * 256 + ch;
;         float kx[4]; shifted4(256 + ch, kx);
;         const float4 kw = *(const float4*)(kkw + ch);
;         const float kkn[4] = {kx[0] * kw.x * kinv, kx[1] * kw.y * kinv, kx[2] * kw.z * kinv, kx[3] * kw.w * kinv};
;         const float4 w0 = *(const float4*)(w0p + d * 256 + ch);
;         const float4 a0 = *(const float4*)(a0p + d * 256 + ch);
;         const float4 ka = *(const float4*)(kap + d * 256 + ch);
;         const float w0a[4] = {w0.x, w0.y, w0.z, w0.w}, a0a[4] = {a0.x, a0.y, a0.z, a0.w}, kaa[4] = {ka.x, ka.y, ka.z, ka.w};
;         float omw[4], kd[4], bb[4];
; #pragma unroll
;         for (int j = 0; j < 4; ++j) {
;           const float xw = -(w0a[j] + aw[ni][j]);
;           const float sp = fmaxf(xw, 0.f) + __logf(1.f + __expf(-fabsf(xw)));
;           const float wlog = -sp - 0.5f;
;           const float e = __expf(wlog);
;           omw[j] = 1.f - __expf(-e);
;           const float a = sigmoidf_(a0a[j] + aa[ni][j]);
.LBB0_845:
	s_lshl_b32 s64, s39, 15
	v_lshl_add_u64 v[34:35], v[70:71], 0, s[64:65]
	v_lshl_add_u64 v[38:39], v[72:73], 0, s[64:65]
	v_lshl_add_u64 v[46:47], v[34:35], 0, v[74:75]
	v_lshl_add_u64 v[56:57], v[34:35], 0, v[76:77]
	v_lshl_add_u64 v[158:159], v[34:35], 0, v[78:79]
	v_lshl_add_u64 v[160:161], v[38:39], 0, v[78:79]
	v_lshl_add_u64 v[164:165], v[34:35], 0, v[80:81]
	flat_load_dwordx4 v[2:5], v[46:47]
	flat_load_dwordx4 v[10:13], v[56:57]
	flat_load_dwordx4 v[26:29], v[158:159]
	flat_load_dwordx4 v[30:33], v[160:161]
	flat_load_dwordx4 v[34:37], v[164:165]
	v_lshl_add_u32 v112, s39, 7, v118
	v_lshl_add_u64 v[48:49], v[38:39], 0, v[74:75]
	ds_read_b128 v[18:21], v112 offset:41760
	ds_read_b128 v[22:25], v112 offset:42016
	flat_load_dwordx4 v[6:9], v[48:49]
	v_lshl_add_u64 v[156:157], v[38:39], 0, v[76:77]
	v_lshl_add_u64 v[166:167], v[38:39], 0, v[80:81]
	flat_load_dwordx4 v[14:17], v[156:157]
	s_and_b64 s[0:1], s[36:37], exec
	s_cselect_b32 s38, s77, 0x8800000
	s_cselect_b32 s40, s3, 0x9900000
	s_waitcnt vmcnt(0) lgkmcnt(0)
	v_mfma_f32_16x16x32_bf16 v[10:13], v[10:13], v[18:21], 0
	v_mfma_f32_16x16x32_bf16 v[38:41], v[26:29], v[18:21], 0
	flat_load_dwordx4 v[26:29], v[166:167]
	v_mfma_f32_16x16x32_bf16 v[42:45], v[30:33], v[22:25], 0
	flat_load_dwordx4 v[30:33], v[46:47] offset:64
	v_mfma_f32_16x16x32_bf16 v[2:5], v[2:5], v[18:21], 0
	v_mfma_f32_16x16x32_bf16 v[34:37], v[34:37], v[18:21], 0
	flat_load_dwordx4 v[18:21], v[48:49] offset:64
	ds_read_b128 v[46:49], v112 offset:41824
	ds_read_b128 v[112:115], v112 offset:42080
	v_mfma_f32_16x16x32_bf16 v[6:9], v[6:9], v[22:25], 0
	v_mfma_f32_16x16x32_bf16 v[14:17], v[14:17], v[22:25], 0
	s_waitcnt vmcnt(0) lgkmcnt(0)
	v_mfma_f32_16x16x32_bf16 v[50:53], v[26:29], v[22:25], 0
	flat_load_dwordx4 v[22:25], v[56:57] offset:64
	v_mfma_f32_16x16x32_bf16 v[30:33], v[30:33], v[46:49], v[2:5]
	s_nop 2
	flat_load_dwordx4 v[2:5], v[156:157] offset:64
	v_mfma_f32_16x16x32_bf16 v[26:29], v[18:21], v[112:115], v[6:9]
	s_nop 2
	flat_load_dwordx4 v[6:9], v[158:159] offset:64
	s_waitcnt vmcnt(0) lgkmcnt(0)
	v_mfma_f32_16x16x32_bf16 v[22:25], v[22:25], v[46:49], v[10:13]
	s_nop 2
	flat_load_dwordx4 v[10:13], v[160:161] offset:64
	v_mfma_f32_16x16x32_bf16 v[18:21], v[2:5], v[112:115], v[14:17]
	flat_load_dwordx4 v[2:5], v[164:165] offset:64
	v_mfma_f32_16x16x32_bf16 v[14:17], v[6:9], v[46:49], v[38:41]
	v_cndmask_b32_e64 v6, 0, 1, s[36:37]
	s_mov_b32 s36, 0x2200000
	s_nop 0
	flat_load_dwordx4 v[38:41], v[166:167] offset:64
	s_cselect_b32 s42, s36, 0x3300000
	s_lshl_b32 s36, s39, 10
	v_cmp_ne_u32_e64 s[0:1], 1, v6
	s_waitcnt vmcnt(0) lgkmcnt(0)
	v_mfma_f32_16x16x32_bf16 v[10:13], v[10:13], v[112:115], v[42:45]
	v_mfma_f32_16x16x32_bf16 v[6:9], v[2:5], v[46:49], v[34:37]
	v_mfma_f32_16x16x32_bf16 v[2:5], v[38:41], v[112:115], v[50:53]
	v_add_u32_e32 v157, s36, v141
	s_nop 0
	ds_read_b64 v[34:35], v140 offset:2832
	ds_read_b64 v[36:37], v140 offset:512
	ds_read_b64 v[38:39], v140 offset:5152
	ds_read_b128 v[46:49], v157 offset:64544
	v_add_u32_e32 v158, s36, v142
	s_waitcnt lgkmcnt(3)
	v_lshlrev_b32_e32 v50, 16, v34
	s_waitcnt lgkmcnt(2)
	v_lshlrev_b32_e32 v52, 16, v36
	s_waitcnt lgkmcnt(1)
	v_lshlrev_b32_e32 v160, 16, v38
	v_and_b32_e32 v53, 0xffff0000, v36
	v_and_b32_e32 v161, 0xffff0000, v38
	v_lshlrev_b32_e32 v114, 16, v37
	v_lshlrev_b32_e32 v112, 16, v39
	v_and_b32_e32 v115, 0xffff0000, v37
	v_and_b32_e32 v113, 0xffff0000, v39
	ds_read_b128 v[36:39], v158
	s_waitcnt lgkmcnt(1)
	v_add_f32_e32 v30, v30, v46
	v_and_b32_e32 v51, 0xffff0000, v34
	v_max_f32_e64 v34, -v30, 0
	v_mul_f32_e64 v30, |v30|, s76
	v_exp_f32_e32 v30, v30
	v_lshlrev_b32_e32 v56, 16, v35
	v_and_b32_e32 v57, 0xffff0000, v35
	v_add_u32_e32 v156, s36, v143
	v_add_f32_e32 v30, 1.0, v30
	v_cmp_gt_f32_e32 vcc, s31, v30
	v_add_f32_e32 v31, v31, v47
	s_waitcnt lgkmcnt(0)
	v_add_f32_e32 v26, v26, v36
	v_cndmask_b32_e64 v35, 0, 32, vcc
	v_ldexp_f32 v30, v30, v35
	v_log_f32_e32 v30, v30
	v_add_f32_e32 v27, v27, v37
	v_mul_f32_e32 v26, 0xbfb8aa3b, v26
	v_mul_f32_e32 v27, 0xbfb8aa3b, v27
	v_mul_f32_e32 v35, 0x3f317217, v30
	v_fma_f32 v35, v30, s33, -v35
	v_fmac_f32_e32 v35, 0x3377d1cf, v30
	v_fmac_f32_e32 v35, 0x3f317217, v30
	v_cmp_lt_f32_e64 s[36:37], |v30|, s71
	v_exp_f32_e32 v26, v26
	v_exp_f32_e32 v27, v27
	v_cndmask_b32_e64 v30, v30, v35, s[36:37]
	v_cndmask_b32_e32 v35, 0, v242, vcc
	v_sub_f32_e32 v30, v30, v35
	v_add_f32_e32 v30, v34, v30
	v_max_f32_e64 v34, -v31, 0
	v_mul_f32_e64 v31, |v31|, s76
	v_exp_f32_e32 v31, v31
	ds_read_b128 v[44:47], v141 offset:55328
	ds_read_b128 v[40:43], v141 offset:59936
	v_pk_add_f32 v[26:27], v[26:27], 1.0 op_sel_hi:[1,0]
	v_pk_add_f32 v[36:37], v[160:161], v[50:51] neg_lo:[0,1] neg_hi:[0,1]
	v_add_f32_e32 v31, 1.0, v31
	v_cmp_gt_f32_e32 vcc, s31, v31
	v_add_f32_e32 v32, v32, v48
	v_add_f32_e32 v33, v33, v49
	v_cndmask_b32_e64 v35, 0, 32, vcc
	v_ldexp_f32 v31, v31, v35
	v_log_f32_e32 v31, v31
	v_add_f32_e32 v28, v28, v38
	v_max_f32_e64 v38, -v33, 0
	v_mul_f32_e64 v33, |v33|, s76
	v_mul_f32_e32 v35, 0x3f317217, v31
	v_fma_f32 v35, v31, s33, -v35
	v_fmac_f32_e32 v35, 0x3377d1cf, v31
	v_fmac_f32_e32 v35, 0x3f317217, v31
	v_cmp_lt_f32_e64 s[36:37], |v31|, s71
	v_exp_f32_e32 v33, v33
	v_add_f32_e32 v29, v29, v39
	v_cndmask_b32_e64 v31, v31, v35, s[36:37]
	v_cndmask_b32_e32 v35, 0, v242, vcc
	v_sub_f32_e32 v31, v31, v35
	v_add_f32_e32 v31, v34, v31
	v_pk_add_f32 v[34:35], v[52:53], v[50:51] neg_lo:[0,1] neg_hi:[0,1]
	v_add_f32_e32 v33, 1.0, v33
	s_waitcnt lgkmcnt(1)
	v_pk_fma_f32 v[34:35], v[34:35], v[44:45], v[50:51]
	s_waitcnt lgkmcnt(0)
; DI unsigned pack2(float a, float b) { float2_t v = {a, b}; bf16x2_t r = __builtin_convertvector(v, bf16x2_t); return __builtin_bit_cast(unsigned, r); }
; DI float sigmoidf_(float x) { return 1.f / (1.f + __expf(-x)); }
; DI void phase_tokB(const Params& p, int l, char* smem) {
;     ...
;       for (int ni = 0; ni < 4; ++ni) {
;         const int ch = wave * 64 + ni * 16 + lq * 4;
;         const size_t o = (size_t)row * 256 + ch;
;         float kx[4]; shifted4(256 + ch, kx);
;         const float4 kw = *(const float4*)(kkw + ch);
;         const float kkn[4] = {kx[0] * kw.x * kinv, kx[1] * kw.y * kinv, kx[2] * kw.z * kinv, kx[3] * kw.w * kinv};
;         const float4 w0 = *(const float4*)(w0p + d * 256 + ch);
;         const float4 a0 = *(const float4*)(a0p + d * 256 + ch);
;         const float4 ka = *(const float4*)(kap + d * 256 + ch);
;         const float w0a[4] = {w0.x, w0.y, w0.z, w0.w}, a0a[4] = {a0.x, a0.y, a0.z, a0.w}, kaa[4] = {ka.x, ka.y, ka.z, ka.w};
;         float omw[4], kd[4], bb[4];
; #pragma unroll
;         for (int j = 0; j < 4; ++j) {
;           const float xw = -(w0a[j] + aw[ni][j]);
;           const float sp = fmaxf(xw, 0.f) + __logf(1.f + __expf(-fabsf(xw)));
;           const float wlog = -sp - 0.5f;
;           const float e = __expf(wlog);
;           omw[j] = 1.f - __expf(-e);
;           const float a = sigmoidf_(a0a[j] + aa[ni][j]);
;           kd[j] = kx[j] * (1.f + (a - 1.f) * kaa[j]);
;           bb[j] = kkn[j] * a;
;         }
;         *(uint2*)(oOMW + o) = make_uint2(pack2(omw[0], omw[1]), pack2(omw[2], omw[3]));
;         *(uint2*)(oKD + o) = make_uint2(pack2(kd[0], kd[1]), pack2(kd[2], kd[3]));
;         *(uint2*)(oB + o) = make_uint2(pack2(bb[0], bb[1]), pack2(bb[2], bb[3]));
;         __builtin_amdgcn_sched_barrier(0);
	v_pk_fma_f32 v[40:41], v[36:37], v[40:41], v[34:35]
	ds_read_b128 v[34:37], v156
	v_mul_f32_e32 v28, 0xbfb8aa3b, v28
	v_rcp_f32_e32 v45, v27
	v_mul_f32_e32 v29, 0xbfb8aa3b, v29
	v_exp_f32_e32 v28, v28
	v_exp_f32_e32 v29, v29
	ds_read_b128 v[50:53], v141 offset:63520
	v_rcp_f32_e32 v44, v26
	s_nop 0
	v_pk_add_f32 v[26:27], v[44:45], -1.0 op_sel_hi:[1,0]
	v_pk_add_f32 v[28:29], v[28:29], 1.0 op_sel_hi:[1,0]
	s_waitcnt lgkmcnt(1)
	v_pk_fma_f32 v[26:27], v[34:35], v[26:27], 1.0 op_sel_hi:[1,1,0]
	s_waitcnt lgkmcnt(0)
	v_pk_mul_f32 v[34:35], v[40:41], v[50:51]
	v_pk_mul_f32 v[26:27], v[40:41], v[26:27]
	v_max_f32_e64 v40, -v32, 0
	v_mul_f32_e64 v32, |v32|, s76
	v_exp_f32_e32 v32, v32
	v_pk_mul_f32 v[34:35], v[110:111], v[34:35]
	v_sub_f32_e32 v30, -0.5, v30
	v_pk_mul_f32 v[34:35], v[34:35], v[44:45]
	v_add_f32_e32 v32, 1.0, v32
	v_cmp_gt_f32_e32 vcc, s31, v32
	v_sub_f32_e32 v31, -0.5, v31
	v_mul_f32_e32 v30, 0x3fb8aa3b, v30
	v_cndmask_b32_e64 v41, 0, 32, vcc
	v_ldexp_f32 v32, v32, v41
	v_log_f32_e32 v32, v32
	v_mul_f32_e32 v31, 0x3fb8aa3b, v31
	v_exp_f32_e32 v30, v30
	v_exp_f32_e32 v31, v31
	v_mul_f32_e32 v41, 0x3f317217, v32
	v_fma_f32 v41, v32, s33, -v41
	v_fmac_f32_e32 v41, 0x3377d1cf, v32
	v_fmac_f32_e32 v41, 0x3f317217, v32
	v_cmp_lt_f32_e64 s[36:37], |v32|, s71
	v_mul_f32_e32 v30, 0xbfb8aa3b, v30
	v_mul_f32_e32 v31, 0xbfb8aa3b, v31
	v_cndmask_b32_e64 v32, v32, v41, s[36:37]
	v_cndmask_b32_e32 v41, 0, v242, vcc
	v_sub_f32_e32 v32, v32, v41
	v_cmp_gt_f32_e32 vcc, s31, v33
	v_add_f32_e32 v32, v40, v32
	v_sub_f32_e32 v32, -0.5, v32
	v_cndmask_b32_e64 v40, 0, 32, vcc
	v_ldexp_f32 v33, v33, v40
	v_log_f32_e32 v33, v33
	v_mul_f32_e32 v32, 0x3fb8aa3b, v32
	v_exp_f32_e32 v32, v32
	v_exp_f32_e32 v30, v30
	v_mul_f32_e32 v40, 0x3f317217, v33
	v_fma_f32 v40, v33, s33, -v40
	v_fmac_f32_e32 v40, 0x3377d1cf, v33
	v_fmac_f32_e32 v40, 0x3f317217, v33
	v_cmp_lt_f32_e64 s[36:37], |v33|, s71
	v_mul_f32_e32 v32, 0xbfb8aa3b, v32
	v_exp_f32_e32 v31, v31
	v_cndmask_b32_e64 v33, v33, v40, s[36:37]
	v_cndmask_b32_e32 v40, 0, v242, vcc
	v_sub_f32_e32 v33, v33, v40
	v_add_f32_e32 v33, v38, v33
	v_pk_add_f32 v[38:39], v[114:115], v[56:57] neg_lo:[0,1] neg_hi:[0,1]
	v_pk_add_f32 v[40:41], v[112:113], v[56:57] neg_lo:[0,1] neg_hi:[0,1]
	v_pk_fma_f32 v[38:39], v[38:39], v[46:47], v[56:57]
	v_sub_f32_e32 v33, -0.5, v33
	v_pk_fma_f32 v[38:39], v[40:41], v[42:43], v[38:39]
	v_mul_f32_e32 v33, 0x3fb8aa3b, v33
	v_exp_f32_e32 v33, v33
	v_exp_f32_e32 v32, v32
	v_rcp_f32_e32 v29, v29
	v_mul_f32_e32 v33, 0xbfb8aa3b, v33
	v_exp_f32_e32 v33, v33
	s_mov_b32 s43, s65
	v_rcp_f32_e32 v28, v28
	s_nop 0
	v_pk_add_f32 v[40:41], v[28:29], -1.0 op_sel_hi:[1,0]
	s_mov_b32 s39, s65
	v_pk_fma_f32 v[36:37], v[36:37], v[40:41], 1.0 op_sel_hi:[1,1,0]
	s_mov_b32 s41, s65
	v_pk_mul_f32 v[36:37], v[38:39], v[36:37]
	v_pk_mul_f32 v[38:39], v[38:39], v[52:53]
	v_pk_add_f32 v[30:31], v[30:31], 1.0 op_sel_hi:[1,0] neg_lo:[1,0] neg_hi:[1,0]
	v_pk_mul_f32 v[38:39], v[110:111], v[38:39]
	v_pk_add_f32 v[32:33], v[32:33], 1.0 op_sel_hi:[1,0] neg_lo:[1,0] neg_hi:[1,0]
	v_pk_mul_f32 v[28:29], v[38:39], v[28:29]
	v_cvt_pk_bf16_f32 v26, v26, v27
	v_cvt_pk_bf16_f32 v27, v36, v37
	v_lshl_add_u64 v[48:49], v[54:55], 0, s[42:43]
	v_cvt_pk_bf16_f32 v30, v30, v31
	v_cvt_pk_bf16_f32 v31, v32, v33
	v_lshl_add_u64 v[46:47], v[54:55], 0, s[38:39]
	flat_store_dwordx2 v[48:49], v[26:27]
	v_cvt_pk_bf16_f32 v26, v34, v35
	v_cvt_pk_bf16_f32 v27, v28, v29
	v_lshl_add_u64 v[50:51], v[54:55], 0, s[40:41]
	flat_store_dwordx2 v[46:47], v[30:31]
	flat_store_dwordx2 v[50:51], v[26:27]
	ds_read_b64 v[26:27], v140 offset:2864
	ds_read_b64 v[28:29], v140 offset:544
	ds_read_b64 v[30:31], v140 offset:5184
	s_waitcnt lgkmcnt(0)
	v_lshlrev_b32_e32 v42, 16, v26
	v_lshlrev_b32_e32 v44, 16, v28
	v_lshlrev_b32_e32 v114, 16, v30
	v_and_b32_e32 v45, 0xffff0000, v28
	v_and_b32_e32 v115, 0xffff0000, v30
	v_lshlrev_b32_e32 v112, 16, v29
	v_lshlrev_b32_e32 v56, 16, v31
	v_and_b32_e32 v113, 0xffff0000, v29
	v_and_b32_e32 v57, 0xffff0000, v31
	ds_read_b128 v[38:41], v157 offset:64608
	ds_read_b128 v[28:31], v158 offset:64
	v_and_b32_e32 v43, 0xffff0000, v26
	v_lshlrev_b32_e32 v52, 16, v27
	v_and_b32_e32 v53, 0xffff0000, v27
	s_waitcnt lgkmcnt(0)
	v_add_f32_e32 v22, v22, v38
	v_max_f32_e64 v26, -v22, 0
	v_mul_f32_e64 v22, |v22|, s76
	v_exp_f32_e32 v22, v22
	v_add_f32_e32 v23, v23, v39
	v_add_f32_e32 v18, v18, v28
	v_add_f32_e32 v19, v19, v29
	v_add_f32_e32 v22, 1.0, v22
	v_cmp_gt_f32_e32 vcc, s31, v22
	v_mul_f32_e32 v18, 0xbfb8aa3b, v18
	v_mul_f32_e32 v19, 0xbfb8aa3b, v19
	v_cndmask_b32_e64 v27, 0, 32, vcc
	v_ldexp_f32 v22, v22, v27
	v_log_f32_e32 v22, v22
	v_exp_f32_e32 v18, v18
	v_exp_f32_e32 v19, v19
	ds_read_b128 v[36:39], v141 offset:55392
	ds_read_b128 v[32:35], v141 offset:60000
	v_mul_f32_e32 v27, 0x3f317217, v22
	v_fma_f32 v27, v22, s33, -v27
	v_fmac_f32_e32 v27, 0x3377d1cf, v22
	v_fmac_f32_e32 v27, 0x3f317217, v22
	v_cmp_lt_f32_e64 s[36:37], |v22|, s71
	v_pk_add_f32 v[18:19], v[18:19], 1.0 op_sel_hi:[1,0]
	v_pk_add_f32 v[28:29], v[114:115], v[42:43] neg_lo:[0,1] neg_hi:[0,1]
	v_cndmask_b32_e64 v22, v22, v27, s[36:37]
	v_cndmask_b32_e32 v27, 0, v242, vcc
	v_sub_f32_e32 v22, v22, v27
	v_add_f32_e32 v22, v26, v22
	v_max_f32_e64 v26, -v23, 0
	v_mul_f32_e64 v23, |v23|, s76
	v_exp_f32_e32 v23, v23
	v_add_f32_e32 v24, v24, v40
	v_add_f32_e32 v25, v25, v41
	v_add_f32_e32 v20, v20, v30
	v_add_f32_e32 v23, 1.0, v23
	v_cmp_gt_f32_e32 vcc, s31, v23
	v_max_f32_e64 v30, -v25, 0
	v_mul_f32_e64 v25, |v25|, s76
	v_cndmask_b32_e64 v27, 0, 32, vcc
	v_ldexp_f32 v23, v23, v27
	v_log_f32_e32 v23, v23
	v_exp_f32_e32 v25, v25
	v_add_f32_e32 v21, v21, v31
	v_mul_f32_e32 v20, 0xbfb8aa3b, v20
	v_mul_f32_e32 v27, 0x3f317217, v23
	v_fma_f32 v27, v23, s33, -v27
	v_fmac_f32_e32 v27, 0x3377d1cf, v23
	v_fmac_f32_e32 v27, 0x3f317217, v23
	v_cmp_lt_f32_e64 s[36:37], |v23|, s71
	v_add_f32_e32 v25, 1.0, v25
	v_mul_f32_e32 v21, 0xbfb8aa3b, v21
	v_cndmask_b32_e64 v23, v23, v27, s[36:37]
	v_cndmask_b32_e32 v27, 0, v242, vcc
	v_sub_f32_e32 v23, v23, v27
	v_add_f32_e32 v23, v26, v23
	v_pk_add_f32 v[26:27], v[44:45], v[42:43] neg_lo:[0,1] neg_hi:[0,1]
	v_exp_f32_e32 v20, v20
	s_waitcnt lgkmcnt(0)
; DI unsigned pack2(float a, float b) { float2_t v = {a, b}; bf16x2_t r = __builtin_convertvector(v, bf16x2_t); return __builtin_bit_cast(unsigned, r); }
; DI float sigmoidf_(float x) { return 1.f / (1.f + __expf(-x)); }
; DI void phase_tokB(const Params& p, int l, char* smem) {
;     ...
;       for (int ni = 0; ni < 4; ++ni) {
;         const int ch = wave * 64 + ni * 16 + lq * 4;
;         const size_t o = (size_t)row * 256 + ch;
;         float kx[4]; shifted4(256 + ch, kx);
;         const float4 kw = *(const float4*)(kkw + ch);
;         const float kkn[4] = {kx[0] * kw.x * kinv, kx[1] * kw.y * kinv, kx[2] * kw.z * kinv, kx[3] * kw.w * kinv};
;         const float4 w0 = *(const float4*)(w0p + d * 256 + ch);
;         const float4 a0 = *(const float4*)(a0p + d * 256 + ch);
;         const float4 ka = *(const float4*)(kap + d * 256 + ch);
;         const float w0a[4] = {w0.x, w0.y, w0.z, w0.w}, a0a[4] = {a0.x, a0.y, a0.z, a0.w}, kaa[4] = {ka.x, ka.y, ka.z, ka.w};
;         float omw[4], kd[4], bb[4];
; #pragma unroll
;         for (int j = 0; j < 4; ++j) {
;           const float xw = -(w0a[j] + aw[ni][j]);
;           const float sp = fmaxf(xw, 0.f) + __logf(1.f + __expf(-fabsf(xw)));
;           const float wlog = -sp - 0.5f;
;           const float e = __expf(wlog);
;           omw[j] = 1.f - __expf(-e);
;           const float a = sigmoidf_(a0a[j] + aa[ni][j]);
;           kd[j] = kx[j] * (1.f + (a - 1.f) * kaa[j]);
;           bb[j] = kkn[j] * a;
;         }
;         *(uint2*)(oOMW + o) = make_uint2(pack2(omw[0], omw[1]), pack2(omw[2], omw[3]));
;         *(uint2*)(oKD + o) = make_uint2(pack2(kd[0], kd[1]), pack2(kd[2], kd[3]));
;         *(uint2*)(oB + o) = make_uint2(pack2(bb[0], bb[1]), pack2(bb[2], bb[3]));
;         __builtin_amdgcn_sched_barrier(0);
	v_pk_fma_f32 v[26:27], v[26:27], v[36:37], v[42:43]
	v_pk_fma_f32 v[32:33], v[28:29], v[32:33], v[26:27]
	ds_read_b128 v[26:29], v156 offset:64
	v_exp_f32_e32 v21, v21
	v_rcp_f32_e32 v37, v19
	v_pk_add_f32 v[20:21], v[20:21], 1.0 op_sel_hi:[1,0]
	v_sub_f32_e32 v22, -0.5, v22
	v_sub_f32_e32 v23, -0.5, v23
	ds_read_b128 v[42:45], v141 offset:63584
	v_rcp_f32_e32 v36, v18
	s_nop 0
	v_pk_add_f32 v[18:19], v[36:37], -1.0 op_sel_hi:[1,0]
	v_mul_f32_e32 v22, 0x3fb8aa3b, v22
	s_waitcnt lgkmcnt(0)
	v_pk_fma_f32 v[18:19], v[26:27], v[18:19], 1.0 op_sel_hi:[1,1,0]
	v_pk_mul_f32 v[26:27], v[32:33], v[42:43]
	v_pk_mul_f32 v[18:19], v[32:33], v[18:19]
	v_max_f32_e64 v32, -v24, 0
	v_mul_f32_e64 v24, |v24|, s76
	v_exp_f32_e32 v24, v24
	v_pk_mul_f32 v[26:27], v[110:111], v[26:27]
	v_mul_f32_e32 v23, 0x3fb8aa3b, v23
	v_pk_mul_f32 v[26:27], v[26:27], v[36:37]
	v_add_f32_e32 v24, 1.0, v24
	v_cmp_gt_f32_e32 vcc, s31, v24
	v_exp_f32_e32 v22, v22
	v_exp_f32_e32 v23, v23
	v_cndmask_b32_e64 v33, 0, 32, vcc
	v_ldexp_f32 v24, v24, v33
	v_log_f32_e32 v24, v24
	v_mul_f32_e32 v22, 0xbfb8aa3b, v22
	v_mul_f32_e32 v23, 0xbfb8aa3b, v23
	v_exp_f32_e32 v22, v22
	v_mul_f32_e32 v33, 0x3f317217, v24
	v_fma_f32 v33, v24, s33, -v33
	v_fmac_f32_e32 v33, 0x3377d1cf, v24
	v_fmac_f32_e32 v33, 0x3f317217, v24
	v_cmp_lt_f32_e64 s[36:37], |v24|, s71
	v_exp_f32_e32 v23, v23
	v_cvt_pk_bf16_f32 v18, v18, v19
	v_cndmask_b32_e64 v24, v24, v33, s[36:37]
	v_cndmask_b32_e32 v33, 0, v242, vcc
	v_sub_f32_e32 v24, v24, v33
	v_cmp_gt_f32_e32 vcc, s31, v25
	v_add_f32_e32 v24, v32, v24
	v_sub_f32_e32 v24, -0.5, v24
	v_cndmask_b32_e64 v32, 0, 32, vcc
	v_ldexp_f32 v25, v25, v32
	v_log_f32_e32 v25, v25
	v_mul_f32_e32 v24, 0x3fb8aa3b, v24
	v_exp_f32_e32 v24, v24
	v_pk_add_f32 v[22:23], v[22:23], 1.0 op_sel_hi:[1,0] neg_lo:[1,0] neg_hi:[1,0]
	v_mul_f32_e32 v32, 0x3f317217, v25
	v_fma_f32 v32, v25, s33, -v32
	v_fmac_f32_e32 v32, 0x3377d1cf, v25
	v_fmac_f32_e32 v32, 0x3f317217, v25
	v_cmp_lt_f32_e64 s[36:37], |v25|, s71
	v_mul_f32_e32 v24, 0xbfb8aa3b, v24
	v_exp_f32_e32 v24, v24
	v_cndmask_b32_e64 v25, v25, v32, s[36:37]
	v_cndmask_b32_e32 v32, 0, v242, vcc
	v_sub_f32_e32 v25, v25, v32
	v_add_f32_e32 v25, v30, v25
	v_pk_add_f32 v[30:31], v[112:113], v[52:53] neg_lo:[0,1] neg_hi:[0,1]
	v_pk_add_f32 v[32:33], v[56:57], v[52:53] neg_lo:[0,1] neg_hi:[0,1]
	v_pk_fma_f32 v[30:31], v[30:31], v[38:39], v[52:53]
	v_sub_f32_e32 v25, -0.5, v25
	v_pk_fma_f32 v[30:31], v[32:33], v[34:35], v[30:31]
	v_mul_f32_e32 v25, 0x3fb8aa3b, v25
	v_exp_f32_e32 v25, v25
	v_cvt_pk_bf16_f32 v22, v22, v23
	v_rcp_f32_e32 v21, v21
	v_mul_f32_e32 v25, 0xbfb8aa3b, v25
	v_exp_f32_e32 v25, v25
	v_rcp_f32_e32 v20, v20
	s_nop 0
	v_pk_add_f32 v[32:33], v[20:21], -1.0 op_sel_hi:[1,0]
	v_pk_add_f32 v[24:25], v[24:25], 1.0 op_sel_hi:[1,0] neg_lo:[1,0] neg_hi:[1,0]
	v_pk_fma_f32 v[28:29], v[28:29], v[32:33], 1.0 op_sel_hi:[1,1,0]
	v_cvt_pk_bf16_f32 v23, v24, v25
	v_pk_mul_f32 v[28:29], v[30:31], v[28:29]
	v_pk_mul_f32 v[30:31], v[30:31], v[44:45]
	v_cvt_pk_bf16_f32 v19, v28, v29
	v_pk_mul_f32 v[30:31], v[110:111], v[30:31]
	flat_store_dwordx2 v[48:49], v[18:19] offset:32
	v_pk_mul_f32 v[20:21], v[30:31], v[20:21]
	v_cvt_pk_bf16_f32 v18, v26, v27
	v_cvt_pk_bf16_f32 v19, v20, v21
	flat_store_dwordx2 v[46:47], v[22:23] offset:32
	flat_store_dwordx2 v[50:51], v[18:19] offset:32
	ds_read_b64 v[18:19], v140 offset:2896
	ds_read_b64 v[20:21], v140 offset:576
	ds_read_b64 v[22:23], v140 offset:5216
	s_waitcnt lgkmcnt(0)
	v_lshlrev_b32_e32 v34, 16, v18
	v_lshlrev_b32_e32 v36, 16, v20
	v_lshlrev_b32_e32 v44, 16, v22
	v_and_b32_e32 v37, 0xffff0000, v20
	v_and_b32_e32 v45, 0xffff0000, v22
	v_lshlrev_b32_e32 v42, 16, v21
	v_lshlrev_b32_e32 v40, 16, v23
	v_and_b32_e32 v43, 0xffff0000, v21
	v_and_b32_e32 v41, 0xffff0000, v23
	ds_read_b128 v[30:33], v157 offset:64672
	ds_read_b128 v[20:23], v158 offset:128
	v_and_b32_e32 v35, 0xffff0000, v18
	v_lshlrev_b32_e32 v38, 16, v19
	v_and_b32_e32 v39, 0xffff0000, v19
	s_waitcnt lgkmcnt(0)
	v_add_f32_e32 v14, v14, v30
	v_max_f32_e64 v18, -v14, 0
	v_mul_f32_e64 v14, |v14|, s76
	v_exp_f32_e32 v14, v14
	v_add_f32_e32 v15, v15, v31
	v_add_f32_e32 v10, v10, v20
	v_add_f32_e32 v11, v11, v21
	v_add_f32_e32 v14, 1.0, v14
	v_cmp_gt_f32_e32 vcc, s31, v14
	v_mul_f32_e32 v10, 0xbfb8aa3b, v10
	v_mul_f32_e32 v11, 0xbfb8aa3b, v11
	v_cndmask_b32_e64 v19, 0, 32, vcc
	v_ldexp_f32 v14, v14, v19
	v_log_f32_e32 v14, v14
	v_exp_f32_e32 v10, v10
	v_exp_f32_e32 v11, v11
	ds_read_b128 v[28:31], v141 offset:55456
	ds_read_b128 v[24:27], v141 offset:60064
	v_mul_f32_e32 v19, 0x3f317217, v14
	v_fma_f32 v19, v14, s33, -v19
	v_fmac_f32_e32 v19, 0x3377d1cf, v14
	v_fmac_f32_e32 v19, 0x3f317217, v14
	v_cmp_lt_f32_e64 s[36:37], |v14|, s71
	v_pk_add_f32 v[10:11], v[10:11], 1.0 op_sel_hi:[1,0]
	v_pk_add_f32 v[20:21], v[44:45], v[34:35] neg_lo:[0,1] neg_hi:[0,1]
	v_cndmask_b32_e64 v14, v14, v19, s[36:37]
	v_cndmask_b32_e32 v19, 0, v242, vcc
	v_sub_f32_e32 v14, v14, v19
	v_add_f32_e32 v14, v18, v14
	v_max_f32_e64 v18, -v15, 0
	v_mul_f32_e64 v15, |v15|, s76
	v_exp_f32_e32 v15, v15
	v_add_f32_e32 v16, v16, v32
	v_add_f32_e32 v17, v17, v33
	v_add_f32_e32 v12, v12, v22
	v_add_f32_e32 v15, 1.0, v15
	v_cmp_gt_f32_e32 vcc, s31, v15
	v_max_f32_e64 v22, -v17, 0
	v_mul_f32_e64 v17, |v17|, s76
	v_cndmask_b32_e64 v19, 0, 32, vcc
	v_ldexp_f32 v15, v15, v19
	v_log_f32_e32 v15, v15
	v_exp_f32_e32 v17, v17
	v_add_f32_e32 v13, v13, v23
	v_mul_f32_e32 v12, 0xbfb8aa3b, v12
	v_mul_f32_e32 v19, 0x3f317217, v15
	v_fma_f32 v19, v15, s33, -v19
	v_fmac_f32_e32 v19, 0x3377d1cf, v15
	v_fmac_f32_e32 v19, 0x3f317217, v15
	v_cmp_lt_f32_e64 s[36:37], |v15|, s71
	v_add_f32_e32 v17, 1.0, v17
	v_mul_f32_e32 v13, 0xbfb8aa3b, v13
	v_cndmask_b32_e64 v15, v15, v19, s[36:37]
	v_cndmask_b32_e32 v19, 0, v242, vcc
	v_sub_f32_e32 v15, v15, v19
	v_add_f32_e32 v15, v18, v15
	v_pk_add_f32 v[18:19], v[36:37], v[34:35] neg_lo:[0,1] neg_hi:[0,1]
	v_exp_f32_e32 v12, v12
	s_waitcnt lgkmcnt(0)
; DI unsigned pack2(float a, float b) { float2_t v = {a, b}; bf16x2_t r = __builtin_convertvector(v, bf16x2_t); return __builtin_bit_cast(unsigned, r); }
; DI float sigmoidf_(float x) { return 1.f / (1.f + __expf(-x)); }
; DI void phase_tokB(const Params& p, int l, char* smem) {
;     ...
;       for (int ni = 0; ni < 4; ++ni) {
;         const int ch = wave * 64 + ni * 16 + lq * 4;
;         const size_t o = (size_t)row * 256 + ch;
;         float kx[4]; shifted4(256 + ch, kx);
;         const float4 kw = *(const float4*)(kkw + ch);
;         const float kkn[4] = {kx[0] * kw.x * kinv, kx[1] * kw.y * kinv, kx[2] * kw.z * kinv, kx[3] * kw.w * kinv};
;         const float4 w0 = *(const float4*)(w0p + d * 256 + ch);
;         const float4 a0 = *(const float4*)(a0p + d * 256 + ch);
;         const float4 ka = *(const float4*)(kap + d * 256 + ch);
;         const float w0a[4] = {w0.x, w0.y, w0.z, w0.w}, a0a[4] = {a0.x, a0.y, a0.z, a0.w}, kaa[4] = {ka.x, ka.y, ka.z, ka.w};
;         float omw[4], kd[4], bb[4];
; #pragma unroll
;         for (int j = 0; j < 4; ++j) {
;           const float xw = -(w0a[j] + aw[ni][j]);
;           const float sp = fmaxf(xw, 0.f) + __logf(1.f + __expf(-fabsf(xw)));
;           const float wlog = -sp - 0.5f;
;           const float e = __expf(wlog);
;           omw[j] = 1.f - __expf(-e);
;           const float a = sigmoidf_(a0a[j] + aa[ni][j]);
;           kd[j] = kx[j] * (1.f + (a - 1.f) * kaa[j]);
;           bb[j] = kkn[j] * a;
;         }
;         *(uint2*)(oOMW + o) = make_uint2(pack2(omw[0], omw[1]), pack2(omw[2], omw[3]));
;         *(uint2*)(oKD + o) = make_uint2(pack2(kd[0], kd[1]), pack2(kd[2], kd[3]));
;         *(uint2*)(oB + o) = make_uint2(pack2(bb[0], bb[1]), pack2(bb[2], bb[3]));
;         __builtin_amdgcn_sched_barrier(0);
	v_pk_fma_f32 v[18:19], v[18:19], v[28:29], v[34:35]
	v_pk_fma_f32 v[24:25], v[20:21], v[24:25], v[18:19]
	ds_read_b128 v[18:21], v156 offset:128
	v_exp_f32_e32 v13, v13
	v_rcp_f32_e32 v29, v11
	v_pk_add_f32 v[12:13], v[12:13], 1.0 op_sel_hi:[1,0]
	v_sub_f32_e32 v14, -0.5, v14
	v_sub_f32_e32 v15, -0.5, v15
	ds_read_b128 v[34:37], v141 offset:63648
	v_rcp_f32_e32 v28, v10
	s_nop 0
	v_pk_add_f32 v[10:11], v[28:29], -1.0 op_sel_hi:[1,0]
	v_mul_f32_e32 v14, 0x3fb8aa3b, v14
	s_waitcnt lgkmcnt(0)
	v_pk_fma_f32 v[10:11], v[18:19], v[10:11], 1.0 op_sel_hi:[1,1,0]
	v_pk_mul_f32 v[18:19], v[24:25], v[34:35]
	v_pk_mul_f32 v[10:11], v[24:25], v[10:11]
	v_max_f32_e64 v24, -v16, 0
	v_mul_f32_e64 v16, |v16|, s76
	v_exp_f32_e32 v16, v16
	v_pk_mul_f32 v[18:19], v[110:111], v[18:19]
	v_mul_f32_e32 v15, 0x3fb8aa3b, v15
	v_pk_mul_f32 v[18:19], v[18:19], v[28:29]
	v_add_f32_e32 v16, 1.0, v16
	v_cmp_gt_f32_e32 vcc, s31, v16
	v_exp_f32_e32 v14, v14
	v_exp_f32_e32 v15, v15
	v_cndmask_b32_e64 v25, 0, 32, vcc
	v_ldexp_f32 v16, v16, v25
	v_log_f32_e32 v16, v16
	v_mul_f32_e32 v14, 0xbfb8aa3b, v14
	v_mul_f32_e32 v15, 0xbfb8aa3b, v15
	v_exp_f32_e32 v14, v14
	v_mul_f32_e32 v25, 0x3f317217, v16
	v_fma_f32 v25, v16, s33, -v25
	v_fmac_f32_e32 v25, 0x3377d1cf, v16
	v_fmac_f32_e32 v25, 0x3f317217, v16
	v_cmp_lt_f32_e64 s[36:37], |v16|, s71
	v_exp_f32_e32 v15, v15
	v_cvt_pk_bf16_f32 v10, v10, v11
	v_cndmask_b32_e64 v16, v16, v25, s[36:37]
	v_cndmask_b32_e32 v25, 0, v242, vcc
	v_sub_f32_e32 v16, v16, v25
	v_cmp_gt_f32_e32 vcc, s31, v17
	v_add_f32_e32 v16, v24, v16
	v_sub_f32_e32 v16, -0.5, v16
	v_cndmask_b32_e64 v24, 0, 32, vcc
	v_ldexp_f32 v17, v17, v24
	v_log_f32_e32 v17, v17
	v_mul_f32_e32 v16, 0x3fb8aa3b, v16
	v_exp_f32_e32 v16, v16
	v_pk_add_f32 v[14:15], v[14:15], 1.0 op_sel_hi:[1,0] neg_lo:[1,0] neg_hi:[1,0]
	v_mul_f32_e32 v24, 0x3f317217, v17
	v_fma_f32 v24, v17, s33, -v24
	v_fmac_f32_e32 v24, 0x3377d1cf, v17
	v_fmac_f32_e32 v24, 0x3f317217, v17
	v_cmp_lt_f32_e64 s[36:37], |v17|, s71
	v_mul_f32_e32 v16, 0xbfb8aa3b, v16
	v_exp_f32_e32 v16, v16
	v_cndmask_b32_e64 v17, v17, v24, s[36:37]
	v_cndmask_b32_e32 v24, 0, v242, vcc
	v_sub_f32_e32 v17, v17, v24
	v_add_f32_e32 v17, v22, v17
	v_pk_add_f32 v[22:23], v[42:43], v[38:39] neg_lo:[0,1] neg_hi:[0,1]
	v_pk_add_f32 v[24:25], v[40:41], v[38:39] neg_lo:[0,1] neg_hi:[0,1]
	v_pk_fma_f32 v[22:23], v[22:23], v[30:31], v[38:39]
	v_sub_f32_e32 v17, -0.5, v17
	v_pk_fma_f32 v[22:23], v[24:25], v[26:27], v[22:23]
	v_mul_f32_e32 v17, 0x3fb8aa3b, v17
	v_exp_f32_e32 v17, v17
	v_cvt_pk_bf16_f32 v14, v14, v15
	v_rcp_f32_e32 v13, v13
	v_mul_f32_e32 v17, 0xbfb8aa3b, v17
	v_exp_f32_e32 v17, v17
	v_rcp_f32_e32 v12, v12
	s_nop 0
	v_pk_add_f32 v[24:25], v[12:13], -1.0 op_sel_hi:[1,0]
	v_pk_add_f32 v[16:17], v[16:17], 1.0 op_sel_hi:[1,0] neg_lo:[1,0] neg_hi:[1,0]
	v_pk_fma_f32 v[20:21], v[20:21], v[24:25], 1.0 op_sel_hi:[1,1,0]
	v_cvt_pk_bf16_f32 v15, v16, v17
	v_pk_mul_f32 v[20:21], v[22:23], v[20:21]
	v_pk_mul_f32 v[22:23], v[22:23], v[36:37]
	v_cvt_pk_bf16_f32 v11, v20, v21
	v_pk_mul_f32 v[22:23], v[110:111], v[22:23]
	flat_store_dwordx2 v[48:49], v[10:11] offset:64
	v_pk_mul_f32 v[12:13], v[22:23], v[12:13]
	v_cvt_pk_bf16_f32 v10, v18, v19
	v_cvt_pk_bf16_f32 v11, v12, v13
	flat_store_dwordx2 v[46:47], v[14:15] offset:64
	flat_store_dwordx2 v[50:51], v[10:11] offset:64
	ds_read_b64 v[10:11], v140 offset:2928
	ds_read_b64 v[12:13], v140 offset:608
	ds_read_b64 v[14:15], v140 offset:5248
	s_waitcnt lgkmcnt(0)
	v_lshlrev_b32_e32 v26, 16, v10
	v_lshlrev_b32_e32 v28, 16, v12
	v_lshlrev_b32_e32 v36, 16, v14
	v_and_b32_e32 v29, 0xffff0000, v12
	v_and_b32_e32 v37, 0xffff0000, v14
	v_lshlrev_b32_e32 v34, 16, v13
	v_lshlrev_b32_e32 v32, 16, v15
	v_and_b32_e32 v35, 0xffff0000, v13
	v_and_b32_e32 v33, 0xffff0000, v15
	ds_read_b128 v[22:25], v157 offset:64736
	ds_read_b128 v[12:15], v158 offset:192
	v_and_b32_e32 v27, 0xffff0000, v10
	v_lshlrev_b32_e32 v30, 16, v11
	v_and_b32_e32 v31, 0xffff0000, v11
	s_waitcnt lgkmcnt(0)
; DI unsigned pack2(float a, float b) { float2_t v = {a, b}; bf16x2_t r = __builtin_convertvector(v, bf16x2_t); return __builtin_bit_cast(unsigned, r); }
; DI float sigmoidf_(float x) { return 1.f / (1.f + __expf(-x)); }
; DI void phase_tokB(const Params& p, int l, char* smem) {
;     ...
;       for (int ni = 0; ni < 4; ++ni) {
;         const int ch = wave * 64 + ni * 16 + lq * 4;
;         const size_t o = (size_t)row * 256 + ch;
;         float kx[4]; shifted4(256 + ch, kx);
;         const float4 kw = *(const float4*)(kkw + ch);
;         const float kkn[4] = {kx[0] * kw.x * kinv, kx[1] * kw.y * kinv, kx[2] * kw.z * kinv, kx[3] * kw.w * kinv};
;         const float4 w0 = *(const float4*)(w0p + d * 256 + ch);
;         const float4 a0 = *(const float4*)(a0p + d * 256 + ch);
;         const float4 ka = *(const float4*)(kap + d * 256 + ch);
;         const float w0a[4] = {w0.x, w0.y, w0.z, w0.w}, a0a[4] = {a0.x, a0.y, a0.z, a0.w}, kaa[4] = {ka.x, ka.y, ka.z, ka.w};
;         float omw[4], kd[4], bb[4];
; #pragma unroll
;         for (int j = 0; j < 4; ++j) {
;           const float xw = -(w0a[j] + aw[ni][j]);
;           const float sp = fmaxf(xw, 0.f) + __logf(1.f + __expf(-fabsf(xw)));
;           const float wlog = -sp - 0.5f;
;           const float e = __expf(wlog);
;           omw[j] = 1.f - __expf(-e);
;           const float a = sigmoidf_(a0a[j] + aa[ni][j]);
;           kd[j] = kx[j] * (1.f + (a - 1.f) * kaa[j]);
;           bb[j] = kkn[j] * a;
;         }
;         *(uint2*)(oOMW + o) = make_uint2(pack2(omw[0], omw[1]), pack2(omw[2], omw[3]));
;         *(uint2*)(oKD + o) = make_uint2(pack2(kd[0], kd[1]), pack2(kd[2], kd[3]));
;         *(uint2*)(oB + o) = make_uint2(pack2(bb[0], bb[1]), pack2(bb[2], bb[3]));
;         __builtin_amdgcn_sched_barrier(0);
;       }
;     }
	v_add_f32_e32 v6, v6, v22
	v_max_f32_e64 v10, -v6, 0
	v_mul_f32_e64 v6, |v6|, s76
	v_exp_f32_e32 v6, v6
	v_add_f32_e32 v7, v7, v23
	v_add_f32_e32 v2, v2, v12
	v_add_f32_e32 v3, v3, v13
	v_add_f32_e32 v6, 1.0, v6
	v_cmp_gt_f32_e32 vcc, s31, v6
	v_mul_f32_e32 v2, 0xbfb8aa3b, v2
	v_mul_f32_e32 v3, 0xbfb8aa3b, v3
	v_cndmask_b32_e64 v11, 0, 32, vcc
	v_ldexp_f32 v6, v6, v11
	v_log_f32_e32 v6, v6
	v_exp_f32_e32 v2, v2
	v_exp_f32_e32 v3, v3
	ds_read_b128 v[20:23], v141 offset:55520
	ds_read_b128 v[16:19], v141 offset:60128
	v_mul_f32_e32 v11, 0x3f317217, v6
	v_fma_f32 v11, v6, s33, -v11
	v_fmac_f32_e32 v11, 0x3377d1cf, v6
	v_fmac_f32_e32 v11, 0x3f317217, v6
	v_cmp_lt_f32_e64 s[36:37], |v6|, s71
	v_pk_add_f32 v[2:3], v[2:3], 1.0 op_sel_hi:[1,0]
	v_pk_add_f32 v[12:13], v[36:37], v[26:27] neg_lo:[0,1] neg_hi:[0,1]
	v_cndmask_b32_e64 v6, v6, v11, s[36:37]
	v_cndmask_b32_e32 v11, 0, v242, vcc
	v_sub_f32_e32 v6, v6, v11
	v_add_f32_e32 v6, v10, v6
	v_max_f32_e64 v10, -v7, 0
	v_mul_f32_e64 v7, |v7|, s76
	v_exp_f32_e32 v7, v7
	v_add_f32_e32 v8, v8, v24
	v_add_f32_e32 v9, v9, v25
	v_add_f32_e32 v4, v4, v14
	v_add_f32_e32 v7, 1.0, v7
	v_cmp_gt_f32_e32 vcc, s31, v7
	v_max_f32_e64 v14, -v9, 0
	v_mul_f32_e64 v9, |v9|, s76
	v_cndmask_b32_e64 v11, 0, 32, vcc
	v_ldexp_f32 v7, v7, v11
	v_log_f32_e32 v7, v7
	v_exp_f32_e32 v9, v9
	v_add_f32_e32 v5, v5, v15
	v_mul_f32_e32 v4, 0xbfb8aa3b, v4
	v_mul_f32_e32 v11, 0x3f317217, v7
	v_fma_f32 v11, v7, s33, -v11
	v_fmac_f32_e32 v11, 0x3377d1cf, v7
	v_fmac_f32_e32 v11, 0x3f317217, v7
	v_cmp_lt_f32_e64 s[36:37], |v7|, s71
	v_add_f32_e32 v9, 1.0, v9
	v_mul_f32_e32 v5, 0xbfb8aa3b, v5
	v_cndmask_b32_e64 v7, v7, v11, s[36:37]
	v_cndmask_b32_e32 v11, 0, v242, vcc
	v_sub_f32_e32 v7, v7, v11
	v_add_f32_e32 v7, v10, v7
	v_pk_add_f32 v[10:11], v[28:29], v[26:27] neg_lo:[0,1] neg_hi:[0,1]
	v_exp_f32_e32 v4, v4
	s_waitcnt lgkmcnt(0)
	v_pk_fma_f32 v[10:11], v[10:11], v[20:21], v[26:27]
	v_pk_fma_f32 v[16:17], v[12:13], v[16:17], v[10:11]
	ds_read_b128 v[10:13], v156 offset:192
	v_exp_f32_e32 v5, v5
	v_rcp_f32_e32 v21, v3
	v_pk_add_f32 v[4:5], v[4:5], 1.0 op_sel_hi:[1,0]
	v_sub_f32_e32 v6, -0.5, v6
	v_sub_f32_e32 v7, -0.5, v7
	ds_read_b128 v[26:29], v141 offset:63712
	v_rcp_f32_e32 v20, v2
	s_nop 0
	v_pk_add_f32 v[2:3], v[20:21], -1.0 op_sel_hi:[1,0]
	v_mul_f32_e32 v6, 0x3fb8aa3b, v6
	s_waitcnt lgkmcnt(0)
	v_pk_fma_f32 v[2:3], v[10:11], v[2:3], 1.0 op_sel_hi:[1,1,0]
	v_pk_mul_f32 v[10:11], v[16:17], v[26:27]
	v_pk_mul_f32 v[2:3], v[16:17], v[2:3]
	v_max_f32_e64 v16, -v8, 0
	v_mul_f32_e64 v8, |v8|, s76
	v_exp_f32_e32 v8, v8
	v_pk_mul_f32 v[10:11], v[110:111], v[10:11]
	v_mul_f32_e32 v7, 0x3fb8aa3b, v7
	v_pk_mul_f32 v[10:11], v[10:11], v[20:21]
	v_add_f32_e32 v8, 1.0, v8
	v_cmp_gt_f32_e32 vcc, s31, v8
	v_exp_f32_e32 v6, v6
	v_exp_f32_e32 v7, v7
	v_cndmask_b32_e64 v17, 0, 32, vcc
	v_ldexp_f32 v8, v8, v17
	v_log_f32_e32 v8, v8
	v_mul_f32_e32 v6, 0xbfb8aa3b, v6
	v_mul_f32_e32 v7, 0xbfb8aa3b, v7
	v_exp_f32_e32 v6, v6
	v_mul_f32_e32 v17, 0x3f317217, v8
	v_fma_f32 v17, v8, s33, -v17
	v_fmac_f32_e32 v17, 0x3377d1cf, v8
	v_fmac_f32_e32 v17, 0x3f317217, v8
	v_cmp_lt_f32_e64 s[36:37], |v8|, s71
	v_exp_f32_e32 v7, v7
	v_cvt_pk_bf16_f32 v2, v2, v3
	v_cndmask_b32_e64 v8, v8, v17, s[36:37]
	v_cndmask_b32_e32 v17, 0, v242, vcc
	v_sub_f32_e32 v8, v8, v17
	v_cmp_gt_f32_e32 vcc, s31, v9
	v_add_f32_e32 v8, v16, v8
	v_sub_f32_e32 v8, -0.5, v8
	v_cndmask_b32_e64 v16, 0, 32, vcc
	v_ldexp_f32 v9, v9, v16
	v_log_f32_e32 v9, v9
	v_mul_f32_e32 v8, 0x3fb8aa3b, v8
	v_exp_f32_e32 v8, v8
	v_pk_add_f32 v[6:7], v[6:7], 1.0 op_sel_hi:[1,0] neg_lo:[1,0] neg_hi:[1,0]
	v_mul_f32_e32 v16, 0x3f317217, v9
	v_fma_f32 v16, v9, s33, -v16
	v_fmac_f32_e32 v16, 0x3377d1cf, v9
	v_fmac_f32_e32 v16, 0x3f317217, v9
	v_cmp_lt_f32_e64 s[36:37], |v9|, s71
	v_mul_f32_e32 v8, 0xbfb8aa3b, v8
	v_exp_f32_e32 v8, v8
	v_cndmask_b32_e64 v9, v9, v16, s[36:37]
	v_cndmask_b32_e32 v16, 0, v242, vcc
	v_sub_f32_e32 v9, v9, v16
	v_add_f32_e32 v9, v14, v9
	v_pk_add_f32 v[14:15], v[34:35], v[30:31] neg_lo:[0,1] neg_hi:[0,1]
	v_pk_add_f32 v[16:17], v[32:33], v[30:31] neg_lo:[0,1] neg_hi:[0,1]
	v_pk_fma_f32 v[14:15], v[14:15], v[22:23], v[30:31]
	v_sub_f32_e32 v9, -0.5, v9
	v_pk_fma_f32 v[14:15], v[16:17], v[18:19], v[14:15]
	v_mul_f32_e32 v9, 0x3fb8aa3b, v9
	v_exp_f32_e32 v9, v9
	v_cvt_pk_bf16_f32 v6, v6, v7
	v_rcp_f32_e32 v5, v5
	v_mul_f32_e32 v9, 0xbfb8aa3b, v9
	v_exp_f32_e32 v9, v9
	v_rcp_f32_e32 v4, v4
	s_nop 0
	v_pk_add_f32 v[16:17], v[4:5], -1.0 op_sel_hi:[1,0]
	v_pk_add_f32 v[8:9], v[8:9], 1.0 op_sel_hi:[1,0] neg_lo:[1,0] neg_hi:[1,0]
	v_pk_fma_f32 v[12:13], v[12:13], v[16:17], 1.0 op_sel_hi:[1,1,0]
	v_cvt_pk_bf16_f32 v7, v8, v9
	v_pk_mul_f32 v[12:13], v[14:15], v[12:13]
	v_pk_mul_f32 v[14:15], v[14:15], v[28:29]
	v_cvt_pk_bf16_f32 v3, v12, v13
	v_pk_mul_f32 v[14:15], v[110:111], v[14:15]
	flat_store_dwordx2 v[48:49], v[2:3] offset:96
	v_pk_mul_f32 v[4:5], v[14:15], v[4:5]
	v_cvt_pk_bf16_f32 v2, v10, v11
	v_cvt_pk_bf16_f32 v3, v4, v5
	flat_store_dwordx2 v[46:47], v[6:7] offset:96
	flat_store_dwordx2 v[50:51], v[2:3] offset:96
	s_mov_b64 s[36:37], 0
	s_and_b64 vcc, exec, s[0:1]
	s_mov_b32 s39, 1
	s_cbranch_vccz .LBB0_845
	s_add_i32 s46, s46, s79
	s_cmpk_gt_i32 s46, 0x87f
	s_cbranch_scc0 .LBB0_784
